# stick-breaking peephole extended: 26 result moves folded into the compensated ln2 multiply by renaming
# speedup vs baseline: 1.0170x; 1.0001x over previous
; #define MFMA(a, b, c) __builtin_amdgcn_mfma_f32_32x32x16_bf16((a), (b), (c), 0, 0, 0)
; DI int crow(int i, int h) { return (i & 3) + 8 * (i >> 2) + 4 * h; }
; DI void qk_tile(const bf16_t* sK, const bf16x8 (&qf)[4], f32x16 (&Sx)[2], int r, int h) {
; #pragma unroll
;   for (int mt = 0; mt < 2; ++mt) {
;     f32x16 a;
; #pragma unroll
;     for (int i = 0; i < 16; ++i) a[i] = 0.f;
; #pragma unroll
;     for (int s = 0; s < 4; ++s) {
;       const bf16x8 k = *(const bf16x8*)(sK + (mt * 32 + r) * 72 + s * 16 + h * 8);
;       a = MFMA(k, qf[s], a);
;     }
;     Sx[mt] = a;
;   }
; template <bool MASKED>
; DI void sb_weights(f32x16 (&Sx)[2], float& carry, int kt, int t, int h) {
; #pragma unroll
;     ...
;         float L[16];
; #pragma unroll
;         for (int i = 0; i < 16; ++i) {
;           const float z = Sx[mt][i];
;           const bool ok = !MASKED || (kt * 64 + mt * 32 + crow(i, h) < t);
;           const float sp = fmaxf(z, 0.f) + __logf(1.f + __expf(-fabsf(z)));
;           L[i] = ok ? -sp : 0.f;
;           Sx[mt][i] = ok ? (z - sp) : NEG;
;         }
.LBB0_277:
	s_add_i32 s44, s80, 1
	v_cmp_le_i32_e64 s[0:1], s44, v177
	s_and_saveexec_b64 s[36:37], s[0:1]
	s_cbranch_execz .LBB0_283
	ds_read_b128 v[0:3], v32
	ds_read_b128 v[4:7], v32 offset:32
	v_cmp_ge_i32_e64 s[0:1], s42, v175
	v_add_f32_e32 v188, 0, v144
	s_waitcnt lgkmcnt(1)
	v_mfma_f32_32x32x16_bf16 v[66:81], v[0:3], v[106:109], 0
	ds_read_b128 v[0:3], v32 offset:4608
	ds_read_b128 v[8:11], v32 offset:4640
	s_waitcnt lgkmcnt(1)
	v_mfma_f32_32x32x16_bf16 v[82:97], v[0:3], v[106:109], 0
	s_waitcnt lgkmcnt(0)
	v_mfma_f32_32x32x16_bf16 v[82:97], v[8:11], v[98:101], v[82:97]
	ds_read_b128 v[0:3], v32 offset:4672
	ds_read_b128 v[8:11], v32 offset:64
	ds_read_b128 v[12:15], v32 offset:96
	ds_read_b128 v[16:19], v32 offset:4704
	v_mfma_f32_32x32x16_bf16 v[66:81], v[4:7], v[98:101], v[66:81]
	s_waitcnt lgkmcnt(3)
	v_mfma_f32_32x32x16_bf16 v[82:97], v[0:3], v[102:105], v[82:97]
	v_and_b32_e32 v1, 64, v208
	v_xor_b32_e32 v0, 32, v208
	v_add_u32_e32 v1, 64, v1
	v_cmp_lt_i32_e64 s[4:5], v0, v1
	s_nop 1
	s_nop 0
	v_cndmask_b32_e64 v0, v208, v0, s[4:5]
	s_waitcnt lgkmcnt(2)
	v_mfma_f32_32x32x16_bf16 v[66:81], v[8:11], v[102:105], v[66:81]
	v_lshlrev_b32_e32 v181, 2, v0
	s_waitcnt lgkmcnt(0)
	v_mfma_f32_32x32x16_bf16 v[82:97], v[16:19], v[110:113], v[82:97]
	v_mfma_f32_32x32x16_bf16 v[66:81], v[12:15], v[110:113], v[66:81]
	s_nop 10
	v_mul_f32_e64 v1, |v82|, s76
	v_mul_f32_e64 v3, |v83|, s76
	v_mul_f32_e64 v17, |v84|, s76
	v_mul_f32_e64 v19, |v85|, s76
	v_mul_f32_e64 v21, |v86|, s76
	v_mul_f32_e64 v23, |v87|, s76
	v_mul_f32_e64 v25, |v88|, s76
	v_mul_f32_e64 v27, |v89|, s76
	v_mul_f32_e64 v29, |v90|, s76
	v_mul_f32_e64 v4, |v91|, s76
	v_mul_f32_e64 v6, |v92|, s76
	v_mul_f32_e64 v31, |v93|, s76
	v_mul_f32_e64 v147, |v94|, s76
	v_mul_f32_e64 v9, |v95|, s76
	v_mul_f32_e64 v11, |v96|, s76
	v_mul_f32_e64 v151, |v97|, s76
	v_mul_f32_e64 v13, |v66|, s76
	v_mul_f32_e64 v15, |v67|, s76
	v_mul_f32_e64 v155, |v68|, s76
	v_exp_f32_e32 v243, v1
	v_exp_f32_e32 v239, v3
	v_exp_f32_e32 v205, v17
	v_exp_f32_e32 v202, v19
	v_exp_f32_e32 v201, v21
	v_exp_f32_e32 v200, v23
	v_exp_f32_e32 v199, v25
	v_exp_f32_e32 v198, v27
	v_exp_f32_e32 v197, v29
	v_exp_f32_e32 v196, v4
	v_exp_f32_e32 v195, v6
	v_exp_f32_e32 v194, v31
	v_exp_f32_e32 v193, v147
	v_exp_f32_e32 v192, v9
	v_exp_f32_e32 v191, v11
	v_exp_f32_e32 v190, v151
	v_exp_f32_e32 v189, v13
	v_exp_f32_e32 v187, v15
	v_exp_f32_e32 v186, v155
	v_max_f32_e32 v0, v82, v82
	v_max_f32_e32 v2, v83, v83
	v_max_f32_e32 v16, v84, v84
	v_max_f32_e32 v18, v85, v85
	v_max_f32_e32 v20, v86, v86
	v_max_f32_e32 v22, v87, v87
	v_max_f32_e32 v24, v88, v88
	v_max_f32_e32 v26, v89, v89
	v_max_f32_e32 v28, v90, v90
	v_max_f32_e32 v30, v91, v91
	v_max_f32_e32 v5, v92, v92
	v_max_f32_e32 v7, v93, v93
	v_max_f32_e32 v145, v94, v94
	v_max_f32_e32 v8, v95, v95
	v_max_f32_e32 v10, v96, v96
	v_max_f32_e32 v149, v97, v97
	v_max_f32_e32 v12, v66, v66
	v_max_f32_e32 v14, v67, v67
	v_max_f32_e32 v153, v68, v68
	v_max_f32_e32 v160, 0, v0
	v_max_f32_e32 v158, 0, v2
	v_max_f32_e32 v156, 0, v16
	v_max_f32_e32 v154, 0, v18
	v_max_f32_e32 v152, 0, v20
	v_max_f32_e32 v150, 0, v22
	v_max_f32_e32 v148, 0, v24
	v_max_f32_e32 v146, 0, v26
	v_max_f32_e32 v172, 0, v28
	v_max_f32_e32 v170, 0, v30
	v_max_f32_e32 v173, 0, v5
	v_max_f32_e32 v171, 0, v7
	v_max_f32_e32 v168, 0, v145
	v_max_f32_e32 v166, 0, v8
	v_max_f32_e32 v169, 0, v10
	v_max_f32_e32 v167, 0, v149
	v_max_f32_e32 v162, 0, v12
	v_max_f32_e32 v164, 0, v14
	v_max_f32_e32 v163, 0, v153
	v_max_f32_e32 v165, v69, v69
	v_mul_f32_e64 v185, |v69|, s76
	v_max_f32_e32 v161, v70, v70
	v_mul_f32_e64 v184, |v70|, s76
	v_max_f32_e32 v159, v71, v71
	v_mul_f32_e64 v183, |v71|, s76
	v_max_f32_e32 v157, v72, v72
	v_mul_f32_e64 v182, |v72|, s76
	v_max_f32_e32 v155, v73, v73
	v_mul_f32_e64 v153, |v73|, s76
	v_max_f32_e32 v151, v74, v74
	v_mul_f32_e64 v149, |v74|, s76
	v_max_f32_e32 v147, v75, v75
	v_mul_f32_e64 v145, |v75|, s76
	s_and_saveexec_b64 s[4:5], s[0:1]
	s_xor_b64 s[38:39], exec, s[4:5]
	s_cbranch_execz .LBB0_280
	v_add_f32_e32 v0, 1.0, v243
	v_add_f32_e32 v2, 1.0, v239
	v_log_f32_e32 v0, v0
	v_log_f32_e32 v2, v2
	v_mul_f32_e32 v1, 0x3f317217, v0
	v_fma_f32 v1, v0, s77, -v1
	v_fmac_f32_e32 v1, 0x3377d1cf, v0
	v_fmac_f32_e32 v1, 0x3f317217, v0
	v_add_f32_e32 v3, 1.0, v205
	v_add_u32_e32 v22, s42, v176
	v_mov_b32_e32 v0, v1
	v_mul_f32_e32 v1, 0x3f317217, v2
	v_fma_f32 v1, v2, s77, -v1
	v_fmac_f32_e32 v1, 0x3377d1cf, v2
	v_log_f32_e32 v3, v3
	v_fmac_f32_e32 v1, 0x3f317217, v2
	v_add_f32_e32 v4, 1.0, v202
	v_subrev_u32_e32 v15, 63, v22
	v_mov_b32_e32 v2, v1
	v_mul_f32_e32 v1, 0x3f317217, v3
	v_fma_f32 v1, v3, s77, -v1
	v_log_f32_e32 v5, v4
	v_fmac_f32_e32 v1, 0x3377d1cf, v3
	v_fmac_f32_e32 v1, 0x3f317217, v3
	v_max_f32_e32 v161, 0, v161
	v_max_f32_e32 v159, 0, v159
	v_mov_b32_e32 v4, v1
	v_mul_f32_e32 v1, 0x3f317217, v5
	v_add_f32_e32 v3, 1.0, v201
	v_fma_f32 v1, v5, s77, -v1
	v_fmac_f32_e32 v1, 0x3377d1cf, v5
	v_fmac_f32_e32 v1, 0x3f317217, v5
	v_log_f32_e32 v3, v3
	v_max_f32_e32 v157, 0, v157
	v_mov_b32_e32 v6, v1
	v_add_f32_e32 v5, 1.0, v200
	v_mul_f32_e32 v8, 0x3f317217, v3
	v_fma_f32 v8, v3, s77, -v8
	v_log_f32_e32 v5, v5
	v_fmac_f32_e32 v8, 0x3377d1cf, v3
	v_fmac_f32_e32 v8, 0x3f317217, v3
	v_max_f32_e32 v155, 0, v155
	v_mul_f32_e32 v10, 0x3f317217, v5
	v_add_f32_e32 v3, 1.0, v199
	v_fma_f32 v10, v5, s77, -v10
	v_fmac_f32_e32 v10, 0x3377d1cf, v5
	v_fmac_f32_e32 v10, 0x3f317217, v5
	v_log_f32_e32 v3, v3
	v_add_f32_e32 v5, 1.0, v198
	v_mul_f32_e32 v16, 0x3f317217, v3
	v_fma_f32 v16, v3, s77, -v16
	v_log_f32_e32 v5, v5
	v_fmac_f32_e32 v16, 0x3377d1cf, v3
	v_fmac_f32_e32 v16, 0x3f317217, v3
; DI int crow(int i, int h) { return (i & 3) + 8 * (i >> 2) + 4 * h; }
; DI float shx32(float v) { return __shfl_xor(v, 32); }
; template <bool MASKED>
; DI void sb_weights(f32x16 (&Sx)[2], float& carry, int kt, int t, int h) {
;     ...
;         for (int i = 0; i < 16; ++i) {
;           const float z = Sx[mt][i];
;           const bool ok = !MASKED || (kt * 64 + mt * 32 + crow(i, h) < t);
;           const float sp = fmaxf(z, 0.f) + __logf(1.f + __expf(-fabsf(z)));
;           L[i] = ok ? -sp : 0.f;
;           Sx[mt][i] = ok ? (z - sp) : NEG;
;         }
;         float G[4], Go[4];
; #pragma unroll
;         for (int gg = 0; gg < 4; ++gg) { G[gg] = (L[4 * gg] + L[4 * gg + 1]) + (L[4 * gg + 2] + L[4 * gg + 3]); Go[gg] = shx32(G[gg]); }
;         float T[4];
;         T[3] = 0.f; T[2] = G[3] + Go[3]; T[1] = T[2] + (G[2] + Go[2]); T[0] = T[1] + (G[1] + Go[1]);
	v_mul_f32_e32 v18, 0x3f317217, v5
	v_fma_f32 v18, v5, s77, -v18
	v_fmac_f32_e32 v18, 0x3377d1cf, v5
	v_fmac_f32_e32 v18, 0x3f317217, v5
	v_add_f32_e32 v3, 1.0, v197
	v_log_f32_e32 v3, v3
	v_add_u32_e32 v1, -15, v22
	v_mul_f32_e32 v5, 0x3f317217, v3
	v_fma_f32 v5, v3, s77, -v5
	v_fmac_f32_e32 v5, 0x3377d1cf, v3
	v_fmac_f32_e32 v5, 0x3f317217, v3
	v_mov_b32_e32 v3, v5
	v_add_f32_e32 v5, 1.0, v196
	v_add_f32_e32 v3, v172, v3
	v_cmp_lt_i32_e64 s[0:1], v1, v130
	v_log_f32_e32 v5, v5
	s_nop 0
	v_cndmask_b32_e64 v1, 0, -v3, s[0:1]
	v_sub_f32_e32 v3, v90, v3
	v_cndmask_b32_e64 v24, v214, v3, s[0:1]
	v_mul_f32_e32 v7, 0x3f317217, v5
	v_fma_f32 v7, v5, s77, -v7
	v_fmac_f32_e32 v7, 0x3377d1cf, v5
	v_add_u32_e32 v3, -14, v22
	v_fmac_f32_e32 v7, 0x3f317217, v5
	v_cmp_lt_i32_e64 s[0:1], v3, v130
	v_add_f32_e32 v3, 1.0, v195
	v_mov_b32_e32 v5, v7
	v_add_f32_e32 v5, v170, v5
	v_log_f32_e32 v3, v3
	v_cndmask_b32_e64 v25, 0, -v5, s[0:1]
	v_sub_f32_e32 v5, v91, v5
	v_cndmask_b32_e64 v90, v214, v5, s[0:1]
	v_mul_f32_e32 v7, 0x3f317217, v3
	v_fma_f32 v7, v3, s77, -v7
	v_fmac_f32_e32 v7, 0x3377d1cf, v3
	v_add_u32_e32 v5, -13, v22
	v_fmac_f32_e32 v7, 0x3f317217, v3
	v_add_f32_e32 v20, v1, v25
	v_cmp_lt_i32_e64 s[0:1], v5, v130
	v_add_f32_e32 v5, 1.0, v194
	v_mov_b32_e32 v3, v7
	v_add_f32_e32 v3, v173, v3
	v_log_f32_e32 v5, v5
	v_cndmask_b32_e64 v26, 0, -v3, s[0:1]
	v_sub_f32_e32 v3, v92, v3
	v_cndmask_b32_e64 v91, v214, v3, s[0:1]
	v_mul_f32_e32 v7, 0x3f317217, v5
	v_fma_f32 v7, v5, s77, -v7
	v_fmac_f32_e32 v7, 0x3377d1cf, v5
	v_add_u32_e32 v3, -12, v22
	v_fmac_f32_e32 v7, 0x3f317217, v5
	v_cmp_lt_i32_e64 s[0:1], v3, v130
	v_add_f32_e32 v3, 1.0, v193
	v_mov_b32_e32 v5, v7
	v_add_f32_e32 v5, v171, v5
	v_log_f32_e32 v3, v3
	v_cndmask_b32_e64 v27, 0, -v5, s[0:1]
	v_sub_f32_e32 v5, v93, v5
	v_cndmask_b32_e64 v92, v214, v5, s[0:1]
	v_mul_f32_e32 v7, 0x3f317217, v3
	v_fma_f32 v7, v3, s77, -v7
	v_fmac_f32_e32 v7, 0x3377d1cf, v3
	v_fmac_f32_e32 v7, 0x3f317217, v3
	v_add_u32_e32 v5, -7, v22
	v_mov_b32_e32 v3, v7
	v_add_f32_e32 v7, 1.0, v192
	v_add_f32_e32 v3, v168, v3
	v_cmp_lt_i32_e64 s[0:1], v5, v130
	v_log_f32_e32 v7, v7
	s_nop 0
	v_cndmask_b32_e64 v5, 0, -v3, s[0:1]
	v_sub_f32_e32 v3, v94, v3
	v_cndmask_b32_e64 v3, v214, v3, s[0:1]
	v_mul_f32_e32 v11, 0x3f317217, v7
	v_fma_f32 v11, v7, s77, -v11
	v_fmac_f32_e32 v11, 0x3377d1cf, v7
	v_fmac_f32_e32 v11, 0x3f317217, v7
	v_add_u32_e32 v9, -6, v22
	v_mov_b32_e32 v7, v11
	v_add_f32_e32 v11, 1.0, v191
	v_add_f32_e32 v7, v166, v7
	v_cmp_lt_i32_e64 s[0:1], v9, v130
	v_log_f32_e32 v11, v11
	s_nop 0
	v_cndmask_b32_e64 v9, 0, -v7, s[0:1]
	v_sub_f32_e32 v7, v95, v7
	v_cndmask_b32_e64 v7, v214, v7, s[0:1]
	v_mul_f32_e32 v13, 0x3f317217, v11
	v_fma_f32 v13, v11, s77, -v13
	v_fmac_f32_e32 v13, 0x3377d1cf, v11
	v_add_u32_e32 v12, -5, v22
	v_fmac_f32_e32 v13, 0x3f317217, v11
	v_add_f32_e32 v5, v5, v9
	v_cmp_lt_i32_e64 s[0:1], v12, v130
	v_add_f32_e32 v12, 1.0, v190
	v_mov_b32_e32 v11, v13
	v_add_f32_e32 v11, v169, v11
	v_log_f32_e32 v12, v12
	v_cndmask_b32_e64 v13, 0, -v11, s[0:1]
	v_sub_f32_e32 v11, v96, v11
	v_cndmask_b32_e64 v11, v214, v11, s[0:1]
	v_mul_f32_e32 v17, 0x3f317217, v12
	v_fma_f32 v17, v12, s77, -v17
	v_fmac_f32_e32 v17, 0x3377d1cf, v12
	v_fmac_f32_e32 v17, 0x3f317217, v12
	v_add_u32_e32 v14, -4, v22
	v_mov_b32_e32 v12, v17
	v_add_f32_e32 v12, v167, v12
	v_cmp_lt_i32_e64 s[0:1], v14, v130
	s_nop 1
	s_nop 0
	v_cndmask_b32_e64 v17, 0, -v12, s[0:1]
	v_add_f32_e32 v14, v13, v17
	v_add_f32_e32 v5, v5, v14
	ds_bpermute_b32 v19, v181, v5
	v_sub_f32_e32 v12, v97, v12
	v_cndmask_b32_e64 v21, v214, v12, s[0:1]
	v_max_f32_e32 v97, v78, v78
	v_max_f32_e32 v97, 0, v97
	s_waitcnt lgkmcnt(0)
	v_cndmask_b32_e32 v1, 0, v19, vcc
	v_add_f32_e32 v1, v188, v1
	v_add_f32_e32 v14, v5, v19
	v_add_f32_e32 v5, v17, v1
	v_add_f32_e32 v1, v21, v1
	v_mul_f32_e32 v1, 0x3fb8aa3b, v1
	v_exp_f32_e32 v31, v1
	v_add_f32_e32 v1, v11, v5
	v_add_f32_e32 v13, v13, v5
	v_mul_f32_e32 v1, 0x3fb8aa3b, v1
	v_exp_f32_e32 v30, v1
	v_add_f32_e32 v1, v7, v13
	v_mul_f32_e32 v1, 0x3fb8aa3b, v1
	v_exp_f32_e32 v29, v1
	v_add_f32_e32 v1, 1.0, v189
	v_add_f32_e32 v9, v9, v13
	v_add_f32_e32 v3, v3, v9
	v_log_f32_e32 v1, v1
	v_mul_f32_e32 v3, 0x3fb8aa3b, v3
	v_exp_f32_e32 v28, v3
	v_exp_f32_e32 v9, v153
	v_mul_f32_e32 v3, 0x3f317217, v1
	v_fma_f32 v3, v1, s77, -v3
	v_fmac_f32_e32 v3, 0x3377d1cf, v1
	v_fmac_f32_e32 v3, 0x3f317217, v1
	v_exp_f32_e32 v11, v149
	v_exp_f32_e32 v13, v145
	v_mov_b32_e32 v1, v3
	v_add_f32_e32 v3, 1.0, v187
	v_add_f32_e32 v1, v162, v1
	v_cmp_lt_i32_e64 s[0:1], v15, v130
	v_log_f32_e32 v3, v3
	s_nop 0
	v_cndmask_b32_e64 v23, 0, -v1, s[0:1]
	v_sub_f32_e32 v1, v66, v1
	v_cndmask_b32_e64 v66, v214, v1, s[0:1]
	v_mul_f32_e32 v5, 0x3f317217, v3
	v_fma_f32 v5, v3, s77, -v5
	v_fmac_f32_e32 v5, 0x3377d1cf, v3
	v_subrev_u32_e32 v1, 62, v22
	v_fmac_f32_e32 v5, 0x3f317217, v3
	v_mul_f32_e64 v17, |v76|, s76
	v_exp_f32_e32 v17, v17
	v_cmp_lt_i32_e64 s[0:1], v1, v130
	v_add_f32_e32 v1, 1.0, v186
	v_mov_b32_e32 v3, v5
	v_add_f32_e32 v3, v164, v3
	v_log_f32_e32 v1, v1
	v_cndmask_b32_e64 v94, 0, -v3, s[0:1]
	v_sub_f32_e32 v3, v67, v3
	v_cndmask_b32_e64 v67, v214, v3, s[0:1]
	v_mul_f32_e32 v5, 0x3f317217, v1
	v_fma_f32 v5, v1, s77, -v5
	v_fmac_f32_e32 v5, 0x3377d1cf, v1
	v_fmac_f32_e32 v5, 0x3f317217, v1
	v_subrev_u32_e32 v3, 61, v22
	v_add_f32_e32 v17, 1.0, v17
	v_mov_b32_e32 v1, v5
	v_exp_f32_e32 v5, v185
	v_cmp_lt_i32_e64 s[0:1], v3, v130
	v_add_f32_e32 v1, v163, v1
	v_max_f32_e32 v153, 0, v151
	v_add_f32_e32 v3, 1.0, v5
	v_cndmask_b32_e64 v95, 0, -v1, s[0:1]
	v_sub_f32_e32 v1, v68, v1
	v_log_f32_e32 v3, v3
	v_cndmask_b32_e64 v68, v214, v1, s[0:1]
; DI int crow(int i, int h) { return (i & 3) + 8 * (i >> 2) + 4 * h; }
; template <bool MASKED>
; DI void sb_weights(f32x16 (&Sx)[2], float& carry, int kt, int t, int h) {
;     ...
;         for (int i = 0; i < 16; ++i) {
;           const float z = Sx[mt][i];
;           const bool ok = !MASKED || (kt * 64 + mt * 32 + crow(i, h) < t);
;           const float sp = fmaxf(z, 0.f) + __logf(1.f + __expf(-fabsf(z)));
;           L[i] = ok ? -sp : 0.f;
;           Sx[mt][i] = ok ? (z - sp) : NEG;
;         }
	v_subrev_u32_e32 v1, 60, v22
	v_max_f32_e32 v5, 0, v165
	v_mul_f32_e32 v7, 0x3f317217, v3
	v_fma_f32 v7, v3, s77, -v7
	v_fmac_f32_e32 v7, 0x3377d1cf, v3
	v_fmac_f32_e32 v7, 0x3f317217, v3
	v_max_f32_e32 v151, 0, v147
	v_add_f32_e32 v23, v23, v94
	v_mov_b32_e32 v3, v7
	v_exp_f32_e32 v7, v184
	v_cmp_lt_i32_e64 s[0:1], v1, v130
	v_add_f32_e32 v3, v5, v3
	v_add_f32_e32 v12, v26, v27
	v_add_f32_e32 v1, 1.0, v7
	v_cndmask_b32_e64 v96, 0, -v3, s[0:1]
	v_sub_f32_e32 v3, v69, v3
	v_log_f32_e32 v1, v1
	v_cndmask_b32_e64 v69, v214, v3, s[0:1]
	v_exp_f32_e32 v5, v183
	v_exp_f32_e32 v7, v182
	v_mul_f32_e32 v3, 0x3f317217, v1
	v_fma_f32 v3, v1, s77, -v3
	v_fmac_f32_e32 v3, 0x3377d1cf, v1
	v_fmac_f32_e32 v3, 0x3f317217, v1
	v_add_f32_e32 v93, v144, v14
	v_mov_b32_e32 v1, v3
	v_add_f32_e32 v3, 1.0, v5
	v_log_f32_e32 v3, v3
	v_mov_b32_e32 v1, v1
	v_pk_add_f32 v[0:1], v[160:161], v[0:1]
	v_mul_f32_e32 v5, 0x3f317217, v3
	v_fma_f32 v5, v3, s77, -v5
	v_fmac_f32_e32 v5, 0x3377d1cf, v3
	v_fmac_f32_e32 v5, 0x3f317217, v3
	v_mov_b32_e32 v3, v5
	v_add_f32_e32 v5, 1.0, v7
	v_log_f32_e32 v5, v5
	v_mov_b32_e32 v3, v3
	v_pk_add_f32 v[2:3], v[158:159], v[2:3]
	v_mul_f32_e32 v7, 0x3f317217, v5
	v_fma_f32 v7, v5, s77, -v7
	v_fmac_f32_e32 v7, 0x3377d1cf, v5
	v_fmac_f32_e32 v7, 0x3f317217, v5
	v_mov_b32_e32 v5, v7
	v_add_f32_e32 v7, 1.0, v9
	v_log_f32_e32 v7, v7
	v_mov_b32_e32 v5, v5
	v_pk_add_f32 v[4:5], v[156:157], v[4:5]
	v_mul_f32_e32 v9, 0x3f317217, v7
	v_fma_f32 v9, v7, s77, -v9
	v_fmac_f32_e32 v9, 0x3377d1cf, v7
	v_fmac_f32_e32 v9, 0x3f317217, v7
	v_or_b32_e32 v156, 10, v15
	v_mov_b32_e32 v7, v9
	v_add_f32_e32 v9, 1.0, v11
	v_log_f32_e32 v9, v9
	v_mov_b32_e32 v7, v7
	v_pk_add_f32 v[6:7], v[154:155], v[6:7]
	v_mul_f32_e32 v11, 0x3f317217, v9
	v_fma_f32 v11, v9, s77, -v11
	v_fmac_f32_e32 v11, 0x3377d1cf, v9
	v_fmac_f32_e32 v11, 0x3f317217, v9
	v_or_b32_e32 v154, 11, v15
	v_mov_b32_e32 v9, v11
	v_add_f32_e32 v11, 1.0, v13
	v_log_f32_e32 v11, v11
	v_mov_b32_e32 v9, v9
	v_pk_add_f32 v[8:9], v[152:153], v[8:9]
	v_mul_f32_e32 v13, 0x3f317217, v11
	v_fma_f32 v13, v11, s77, -v13
	v_fmac_f32_e32 v13, 0x3377d1cf, v11
	v_fmac_f32_e32 v13, 0x3f317217, v11
	v_or_b32_e32 v152, 16, v15
	v_mov_b32_e32 v11, v13
	v_max_f32_e32 v13, v76, v76
	v_log_f32_e32 v17, v17
	v_mul_f32_e64 v19, |v77|, s76
	v_exp_f32_e32 v19, v19
	v_max_f32_e32 v149, 0, v13
	v_mul_f32_e32 v13, 0x3f317217, v17
	v_fma_f32 v13, v17, s77, -v13
	v_fmac_f32_e32 v13, 0x3377d1cf, v17
	v_fmac_f32_e32 v13, 0x3f317217, v17
	v_add_f32_e32 v19, 1.0, v19
	v_pk_add_f32 v[10:11], v[150:151], v[10:11]
	v_mov_b32_e32 v17, v13
	v_max_f32_e32 v13, v77, v77
	v_log_f32_e32 v19, v19
	v_max_f32_e32 v147, 0, v13
	v_mul_f32_e64 v21, |v78|, s76
	v_exp_f32_e32 v21, v21
	v_mul_f32_e32 v13, 0x3f317217, v19
	v_fma_f32 v13, v19, s77, -v13
	v_fmac_f32_e32 v13, 0x3377d1cf, v19
	v_fmac_f32_e32 v13, 0x3f317217, v19
	v_or_b32_e32 v150, 17, v15
	v_or_b32_e32 v151, 19, v15
	v_mov_b32_e32 v19, v13
	v_add_f32_e32 v13, 1.0, v21
	v_log_f32_e32 v13, v13
	v_subrev_u32_e32 v21, 39, v22
	v_mul_f32_e32 v145, 0x3f317217, v13
	v_fma_f32 v145, v13, s77, -v145
	v_fmac_f32_e32 v145, 0x3377d1cf, v13
	v_fmac_f32_e32 v145, 0x3f317217, v13
	v_mov_b32_e32 v13, v145
	v_add_f32_e32 v13, v97, v13
	v_mul_f32_e64 v97, |v79|, s76
	v_exp_f32_e32 v97, v97
	v_cmp_lt_i32_e64 s[0:1], v21, v130
	s_nop 1
	s_nop 0
	v_cndmask_b32_e64 v21, 0, -v13, s[0:1]
	v_sub_f32_e32 v13, v78, v13
	v_cndmask_b32_e64 v162, v214, v13, s[0:1]
	v_add_f32_e32 v13, 1.0, v97
	v_max_f32_e32 v97, v79, v79
	v_max_f32_e32 v97, 0, v97
	v_log_f32_e32 v13, v13
	v_subrev_u32_e32 v78, 38, v22
	v_mul_f32_e32 v145, 0x3f317217, v13
	v_fma_f32 v145, v13, s77, -v145
	v_fmac_f32_e32 v145, 0x3377d1cf, v13
	v_fmac_f32_e32 v145, 0x3f317217, v13
	v_mov_b32_e32 v13, v145
	v_add_f32_e32 v97, v97, v13
	v_mul_f32_e64 v13, |v80|, s76
	v_exp_f32_e32 v145, v13
	v_cmp_lt_i32_e64 s[0:1], v78, v130
	v_sub_f32_e32 v78, v79, v97
	s_nop 0
	v_cndmask_b32_e64 v13, 0, -v97, s[0:1]
	v_cndmask_b32_e64 v97, v214, v78, s[0:1]
	v_add_f32_e32 v78, 1.0, v145
	v_max_f32_e32 v145, v80, v80
	v_max_f32_e32 v145, 0, v145
	v_log_f32_e32 v78, v78
	v_subrev_u32_e32 v79, 37, v22
	v_subrev_u32_e32 v22, 36, v22
	v_pk_add_f32 v[20:21], v[20:21], v[12:13]
	v_mul_f32_e32 v163, 0x3f317217, v78
	v_fma_f32 v163, v78, s77, -v163
	v_fmac_f32_e32 v163, 0x3377d1cf, v78
	v_fmac_f32_e32 v163, 0x3f317217, v78
	v_mov_b32_e32 v78, v163
	v_add_f32_e32 v78, v145, v78
	v_mul_f32_e64 v145, |v81|, s76
	v_exp_f32_e32 v145, v145
	v_cmp_lt_i32_e64 s[0:1], v79, v130
	s_nop 1
	s_nop 0
	v_cndmask_b32_e64 v163, 0, -v78, s[0:1]
	v_sub_f32_e32 v78, v80, v78
	v_cndmask_b32_e64 v164, v214, v78, s[0:1]
	v_add_f32_e32 v78, 1.0, v145
	v_log_f32_e32 v78, v78
	v_max_f32_e32 v79, v81, v81
	v_max_f32_e32 v79, 0, v79
	v_mul_f32_e32 v80, 0x3f317217, v78
	v_fma_f32 v80, v78, s77, -v80
	v_fmac_f32_e32 v80, 0x3377d1cf, v78
	v_fmac_f32_e32 v80, 0x3f317217, v78
	v_mov_b32_e32 v78, v80
	v_add_f32_e32 v78, v79, v78
	v_add_f32_e32 v79, v95, v96
	v_add_f32_e32 v23, v23, v79
	ds_bpermute_b32 v80, v181, v23
	v_cmp_lt_i32_e64 s[0:1], v22, v130
	v_sub_f32_e32 v22, v81, v78
	s_waitcnt lgkmcnt(0)
; DI float shx32(float v) { return __shfl_xor(v, 32); }
; template <bool MASKED>
; DI void sb_weights(f32x16 (&Sx)[2], float& carry, int kt, int t, int h) {
;     ...
;         float G[4], Go[4];
; #pragma unroll
;         for (int gg = 0; gg < 4; ++gg) { G[gg] = (L[4 * gg] + L[4 * gg + 1]) + (L[4 * gg + 2] + L[4 * gg + 3]); Go[gg] = shx32(G[gg]); }
;         float T[4];
;         T[3] = 0.f; T[2] = G[3] + Go[3]; T[1] = T[2] + (G[2] + Go[2]); T[0] = T[1] + (G[1] + Go[1]);
;         const float tot = T[0] + (G[0] + Go[0]);
; #pragma unroll
;         for (int gg = 0; gg < 4; ++gg) {
;           const float s3 = carry + T[gg] + (h ? 0.f : Go[gg]);
;           const float s2 = s3 + L[4 * gg + 3], s1 = s2 + L[4 * gg + 2], s0 = s1 + L[4 * gg + 1];
;           Sx[mt][4 * gg + 3] = __expf(Sx[mt][4 * gg + 3] + s3);
;           Sx[mt][4 * gg + 2] = __expf(Sx[mt][4 * gg + 2] + s2);
;           Sx[mt][4 * gg + 1] = __expf(Sx[mt][4 * gg + 1] + s1);
;           Sx[mt][4 * gg + 0] = __expf(Sx[mt][4 * gg + 0] + s0);
;         }
;         carry += tot;
	v_add_f32_e32 v145, v23, v80
	v_cndmask_b32_e64 v165, 0, -v78, s[0:1]
	v_or_b32_e32 v78, 32, v15
	v_cndmask_b32_e64 v166, v214, v22, s[0:1]
	v_cndmask_b32_e32 v167, 0, v80, vcc
	v_sub_f32_e32 v22, v82, v0
	v_cmp_lt_i32_e64 s[4:5], v78, v130
	v_or_b32_e32 v80, 33, v15
	v_cmp_lt_i32_e64 s[6:7], v80, v130
	v_cndmask_b32_e64 v168, v214, v22, s[4:5]
	v_sub_f32_e32 v22, v83, v2
	v_or_b32_e32 v80, 34, v15
	v_cndmask_b32_e64 v169, v214, v22, s[6:7]
	v_sub_f32_e32 v22, v84, v4
	v_cmp_lt_i32_e64 s[8:9], v80, v130
	v_or_b32_e32 v80, 35, v15
	v_cmp_lt_i32_e64 s[10:11], v80, v130
	v_cndmask_b32_e64 v170, v214, v22, s[8:9]
	v_sub_f32_e32 v22, v85, v6
	v_or_b32_e32 v80, 40, v15
	v_cndmask_b32_e64 v171, v214, v22, s[10:11]
	v_sub_f32_e32 v22, v86, v8
	v_cmp_lt_i32_e64 s[12:13], v80, v130
	v_or_b32_e32 v80, 41, v15
	v_cmp_lt_i32_e64 s[14:15], v80, v130
	v_cndmask_b32_e64 v172, v214, v22, s[12:13]
	v_sub_f32_e32 v22, v87, v10
	v_pk_add_f32 v[80:81], v[148:149], v[16:17]
	v_or_b32_e32 v17, 42, v15
	v_or_b32_e32 v23, 8, v15
	v_or_b32_e32 v78, 9, v15
	v_cndmask_b32_e64 v173, v214, v22, s[14:15]
	v_sub_f32_e32 v16, v88, v80
	v_or_b32_e32 v22, 18, v15
	v_cmp_lt_i32_e64 s[16:17], v17, v130
	v_pk_add_f32 v[82:83], v[146:147], v[18:19]
	v_or_b32_e32 v15, 43, v15
	v_cndmask_b32_e64 v182, v214, v16, s[16:17]
	v_sub_f32_e32 v16, v89, v82
	v_cmp_lt_i32_e64 s[18:19], v15, v130
	v_cndmask_b32_e64 v88, 0, -v6, s[10:11]
	v_cmp_lt_i32_e64 s[10:11], v152, v131
	v_cndmask_b32_e64 v183, v214, v16, s[18:19]
	v_cndmask_b32_e64 v16, 0, -v0, s[4:5]
	v_cmp_lt_i32_e64 s[4:5], v78, v131
	ds_bpermute_b32 v78, v181, v20
	v_cndmask_b32_e64 v18, 0, -v8, s[12:13]
	v_cmp_lt_i32_e64 s[12:13], v150, v131
	v_cndmask_b32_e64 v146, 0, -v10, s[14:15]
	v_cmp_lt_i32_e64 s[14:15], v22, v131
	v_cndmask_b32_e64 v148, 0, -v80, s[16:17]
	v_cmp_lt_i32_e64 s[16:17], v151, v131
	v_cndmask_b32_e64 v19, 0, -v9, s[10:11]
	v_cndmask_b32_e64 v147, 0, -v11, s[12:13]
	v_cndmask_b32_e64 v149, 0, -v81, s[14:15]
	v_cndmask_b32_e64 v151, 0, -v83, s[16:17]
	v_cndmask_b32_e64 v150, 0, -v82, s[18:19]
	v_add_f32_e32 v79, v163, v165
	v_cmp_lt_i32_e64 s[0:1], v23, v131
	v_cndmask_b32_e64 v84, 0, -v2, s[6:7]
	v_cmp_lt_i32_e64 s[6:7], v156, v131
	v_cndmask_b32_e64 v86, 0, -v4, s[8:9]
	v_cmp_lt_i32_e64 s[8:9], v154, v131
	v_pk_add_f32 v[18:19], v[18:19], v[146:147]
	v_pk_add_f32 v[22:23], v[148:149], v[150:151]
	v_cndmask_b32_e64 v17, 0, -v1, s[0:1]
	v_cndmask_b32_e64 v85, 0, -v3, s[4:5]
	v_cndmask_b32_e64 v87, 0, -v5, s[6:7]
	v_cndmask_b32_e64 v89, 0, -v7, s[8:9]
	v_pk_add_f32 v[18:19], v[18:19], v[22:23]
	s_waitcnt lgkmcnt(0)
	v_pk_add_f32 v[20:21], v[20:21], v[78:79]
	v_pk_add_f32 v[16:17], v[16:17], v[84:85]
	ds_bpermute_b32 v152, v181, v18
	ds_bpermute_b32 v15, v181, v21
	ds_bpermute_b32 v153, v181, v19
	v_pk_add_f32 v[22:23], v[86:87], v[88:89]
	s_waitcnt lgkmcnt(1)
	v_pk_add_f32 v[158:159], v[20:21], v[14:15]
	v_pk_add_f32 v[154:155], v[16:17], v[22:23]
	ds_bpermute_b32 v156, v181, v154
	s_waitcnt lgkmcnt(1)
	v_pk_add_f32 v[16:17], v[18:19], v[152:153]
	ds_bpermute_b32 v157, v181, v155
	v_pk_add_f32 v[160:161], v[16:17], v[158:159]
	s_waitcnt lgkmcnt(1)
	v_cndmask_b32_e32 v2, 0, v156, vcc
	v_add_f32_e32 v0, v144, v160
	v_add_f32_e32 v0, v2, v0
	v_add_f32_e32 v2, v88, v0
	v_add_f32_e32 v0, v171, v0
	v_mul_f32_e32 v0, 0x3fb8aa3b, v0
	v_exp_f32_e32 v19, v0
	v_add_f32_e32 v0, v170, v2
	v_add_f32_e32 v4, v86, v2
	v_mul_f32_e32 v0, 0x3fb8aa3b, v0
	v_exp_f32_e32 v18, v0
	v_add_f32_e32 v0, v169, v4
	v_add_f32_e32 v6, v84, v4
	v_mul_f32_e32 v0, 0x3fb8aa3b, v0
	v_exp_f32_e32 v17, v0
	v_add_f32_e32 v0, v168, v6
	v_mul_f32_e32 v0, 0x3fb8aa3b, v0
	v_exp_f32_e32 v16, v0
	v_add_f32_e32 v0, v144, v158
	v_cndmask_b32_e32 v2, 0, v152, vcc
	v_add_f32_e32 v0, v2, v0
	v_add_f32_e32 v2, v150, v0
	v_add_f32_e32 v0, v183, v0
	v_mul_f32_e32 v0, 0x3fb8aa3b, v0
	v_exp_f32_e32 v23, v0
	v_add_f32_e32 v0, v182, v2
	v_add_f32_e32 v4, v148, v2
	v_mul_f32_e32 v0, 0x3fb8aa3b, v0
	v_exp_f32_e32 v22, v0
	v_add_f32_e32 v0, v173, v4
	v_add_f32_e32 v6, v146, v4
	v_mul_f32_e32 v0, 0x3fb8aa3b, v0
	v_exp_f32_e32 v21, v0
	v_add_f32_e32 v0, v172, v6
	v_mul_f32_e32 v0, 0x3fb8aa3b, v0
	v_exp_f32_e32 v20, v0
	v_cndmask_b32_e32 v0, 0, v78, vcc
	v_add_f32_e32 v0, v0, v93
	v_add_f32_e32 v2, v27, v0
	v_add_f32_e32 v0, v92, v0
	v_mul_f32_e32 v0, 0x3fb8aa3b, v0
	v_exp_f32_e32 v27, v0
	v_add_f32_e32 v0, v91, v2
	v_add_f32_e32 v4, v26, v2
	v_mul_f32_e32 v0, 0x3fb8aa3b, v0
	v_exp_f32_e32 v26, v0
	v_add_f32_e32 v0, v90, v4
	v_add_f32_e32 v6, v25, v4
	v_mul_f32_e32 v0, 0x3fb8aa3b, v0
	v_exp_f32_e32 v25, v0
	v_add_f32_e32 v0, v24, v6
	v_mul_f32_e32 v0, 0x3fb8aa3b, v0
	v_exp_f32_e32 v24, v0
	v_sub_f32_e32 v0, v70, v1
	v_cndmask_b32_e64 v4, v214, v0, s[0:1]
	v_sub_f32_e32 v0, v71, v3
	v_cndmask_b32_e64 v8, v214, v0, s[4:5]
	v_sub_f32_e32 v0, v72, v5
	v_cndmask_b32_e64 v5, v214, v0, s[6:7]
	v_sub_f32_e32 v0, v73, v7
	v_cndmask_b32_e64 v6, v214, v0, s[8:9]
	v_sub_f32_e32 v0, v74, v9
	v_cndmask_b32_e64 v12, v214, v0, s[10:11]
	v_sub_f32_e32 v0, v75, v11
	v_cndmask_b32_e64 v9, v214, v0, s[12:13]
	v_sub_f32_e32 v0, v76, v81
	v_cndmask_b32_e64 v10, v214, v0, s[14:15]
	v_sub_f32_e32 v0, v77, v83
	v_cndmask_b32_e64 v11, v214, v0, s[16:17]
	s_waitcnt lgkmcnt(0)
; DI int crow(int i, int h) { return (i & 3) + 8 * (i >> 2) + 4 * h; }
; DI float shx32(float v) { return __shfl_xor(v, 32); }
; template <bool MASKED>
; DI void sb_weights(f32x16 (&Sx)[2], float& carry, int kt, int t, int h) {
;     ...
;         for (int i = 0; i < 16; ++i) {
;           const float z = Sx[mt][i];
;           const bool ok = !MASKED || (kt * 64 + mt * 32 + crow(i, h) < t);
;           const float sp = fmaxf(z, 0.f) + __logf(1.f + __expf(-fabsf(z)));
;           L[i] = ok ? -sp : 0.f;
;           Sx[mt][i] = ok ? (z - sp) : NEG;
;         }
;     ...
;         for (int gg = 0; gg < 4; ++gg) { G[gg] = (L[4 * gg] + L[4 * gg + 1]) + (L[4 * gg + 2] + L[4 * gg + 3]); Go[gg] = shx32(G[gg]); }
;         float T[4];
;         T[3] = 0.f; T[2] = G[3] + Go[3]; T[1] = T[2] + (G[2] + Go[2]); T[0] = T[1] + (G[1] + Go[1]);
;         const float tot = T[0] + (G[0] + Go[0]);
; #pragma unroll
;         for (int gg = 0; gg < 4; ++gg) {
;           const float s3 = carry + T[gg] + (h ? 0.f : Go[gg]);
;           const float s2 = s3 + L[4 * gg + 3], s1 = s2 + L[4 * gg + 2], s0 = s1 + L[4 * gg + 1];
;           Sx[mt][4 * gg + 3] = __expf(Sx[mt][4 * gg + 3] + s3);
;           Sx[mt][4 * gg + 2] = __expf(Sx[mt][4 * gg + 2] + s2);
;           Sx[mt][4 * gg + 1] = __expf(Sx[mt][4 * gg + 1] + s1);
;           Sx[mt][4 * gg + 0] = __expf(Sx[mt][4 * gg + 0] + s0);
;         }
;         carry += tot;
	v_pk_add_f32 v[0:1], v[154:155], v[156:157]
	s_nop 0
	v_pk_add_f32 v[0:1], v[0:1], v[160:161]
	s_nop 0
	v_pk_add_f32 v[70:71], v[144:145], v[0:1]
	s_nop 0
	v_add_f32_e32 v0, v70, v1
	v_add_f32_e32 v0, v167, v0
	v_add_f32_e32 v1, v96, v0
	v_add_f32_e32 v0, v69, v0
	v_mul_f32_e32 v0, 0x3fb8aa3b, v0
	v_exp_f32_e32 v3, v0
	v_add_f32_e32 v0, v68, v1
	v_add_f32_e32 v7, v95, v1
	v_mul_f32_e32 v0, 0x3fb8aa3b, v0
	v_exp_f32_e32 v2, v0
	v_add_f32_e32 v0, v67, v7
	v_add_f32_e32 v14, v94, v7
	v_mul_f32_e32 v0, 0x3fb8aa3b, v0
	v_exp_f32_e32 v1, v0
	v_add_f32_e32 v0, v66, v14
	v_add_f32_e32 v7, v70, v161
	v_cndmask_b32_e32 v14, 0, v157, vcc
	v_add_f32_e32 v7, v14, v7
	v_add_f32_e32 v14, v89, v7
	v_add_f32_e32 v6, v6, v7
	v_add_f32_e32 v5, v5, v14
	v_add_f32_e32 v66, v87, v14
	v_mul_f32_e32 v6, 0x3fb8aa3b, v6
	v_mul_f32_e32 v5, 0x3fb8aa3b, v5
	v_exp_f32_e32 v7, v6
	v_exp_f32_e32 v6, v5
	v_add_f32_e32 v5, v8, v66
	v_add_f32_e32 v8, v159, v70
	v_cndmask_b32_e32 v14, 0, v153, vcc
	v_add_f32_e32 v8, v14, v8
	v_add_f32_e32 v14, v151, v8
	v_add_f32_e32 v8, v11, v8
	v_mul_f32_e32 v8, 0x3fb8aa3b, v8
	v_exp_f32_e32 v11, v8
	v_add_f32_e32 v8, v10, v14
	v_add_f32_e32 v67, v85, v66
	v_add_f32_e32 v66, v149, v14
	v_mul_f32_e32 v8, 0x3fb8aa3b, v8
	v_exp_f32_e32 v10, v8
	v_add_f32_e32 v8, v9, v66
	v_add_f32_e32 v4, v4, v67
	v_add_f32_e32 v67, v147, v66
	v_mul_f32_e32 v8, 0x3fb8aa3b, v8
	v_exp_f32_e32 v9, v8
	v_add_f32_e32 v8, v12, v67
	v_add_f32_e32 v12, 0, v70
	v_cndmask_b32_e32 v14, 0, v15, vcc
	v_add_f32_e32 v12, v14, v12
	v_add_f32_e32 v14, v165, v12
	v_add_f32_e32 v12, v166, v12
	v_mul_f32_e32 v12, 0x3fb8aa3b, v12
	v_exp_f32_e32 v15, v12
	v_add_f32_e32 v12, v164, v14
	v_add_f32_e32 v66, v163, v14
	v_mul_f32_e32 v12, 0x3fb8aa3b, v12
	v_exp_f32_e32 v14, v12
	v_add_f32_e32 v12, v97, v66
	v_add_f32_e32 v67, v13, v66
	v_mul_f32_e32 v12, 0x3fb8aa3b, v12
	v_exp_f32_e32 v13, v12
	v_add_f32_e32 v12, v162, v67
	v_mul_f32_e32 v0, 0x3fb8aa3b, v0
	v_mul_f32_e32 v5, 0x3fb8aa3b, v5
	v_mul_f32_e32 v4, 0x3fb8aa3b, v4
	v_mul_f32_e32 v8, 0x3fb8aa3b, v8
	v_mul_f32_e32 v12, 0x3fb8aa3b, v12
	v_exp_f32_e32 v0, v0
	v_exp_f32_e32 v5, v5
	v_exp_f32_e32 v4, v4
	v_exp_f32_e32 v8, v8
	v_exp_f32_e32 v12, v12
	v_add_f32_e32 v144, v70, v71
.LBB0_280:
	s_andn2_saveexec_b64 s[6:7], s[38:39]
	s_cbranch_execz .LBB0_282
	v_add_f32_e32 v0, 1.0, v243
	v_mov_b32_e32 v30, v91
	v_max_f32_e32 v165, 0, v165
	v_log_f32_e32 v0, v0
	v_max_f32_e32 v161, 0, v161
	v_max_f32_e32 v159, 0, v159
	v_max_f32_e32 v157, 0, v157
	v_mul_f32_e32 v1, 0x3f317217, v0
	v_fma_f32 v1, v0, s77, -v1
	v_fmac_f32_e32 v1, 0x3377d1cf, v0
	v_fmac_f32_e32 v1, 0x3f317217, v0
	v_max_f32_e32 v155, 0, v155
	v_mov_b32_e32 v0, v1
	v_add_f32_e32 v1, 1.0, v239
	v_log_f32_e32 v1, v1
	s_nop 0
	v_mul_f32_e32 v2, 0x3f317217, v1
	v_fma_f32 v2, v1, s77, -v2
	v_fmac_f32_e32 v2, 0x3377d1cf, v1
	v_fmac_f32_e32 v2, 0x3f317217, v1
	v_add_f32_e32 v1, 1.0, v205
	v_log_f32_e32 v1, v1
	s_nop 0
	v_mul_f32_e32 v4, 0x3f317217, v1
	v_fma_f32 v4, v1, s77, -v4
	v_fmac_f32_e32 v4, 0x3377d1cf, v1
	v_fmac_f32_e32 v4, 0x3f317217, v1
	v_add_f32_e32 v1, 1.0, v202
	v_log_f32_e32 v1, v1
	s_nop 0
	v_mul_f32_e32 v6, 0x3f317217, v1
	v_fma_f32 v6, v1, s77, -v6
	v_fmac_f32_e32 v6, 0x3377d1cf, v1
	v_fmac_f32_e32 v6, 0x3f317217, v1
	v_add_f32_e32 v1, 1.0, v201
	v_log_f32_e32 v1, v1
	s_nop 0
	v_mul_f32_e32 v8, 0x3f317217, v1
	v_fma_f32 v8, v1, s77, -v8
	v_fmac_f32_e32 v8, 0x3377d1cf, v1
	v_fmac_f32_e32 v8, 0x3f317217, v1
	v_add_f32_e32 v1, 1.0, v200
	v_log_f32_e32 v1, v1
	s_nop 0
	v_mul_f32_e32 v10, 0x3f317217, v1
	v_fma_f32 v10, v1, s77, -v10
	v_fmac_f32_e32 v10, 0x3377d1cf, v1
	v_fmac_f32_e32 v10, 0x3f317217, v1
	v_add_f32_e32 v1, 1.0, v199
	v_log_f32_e32 v1, v1
	s_nop 0
	v_mul_f32_e32 v12, 0x3f317217, v1
	v_fma_f32 v12, v1, s77, -v12
	v_fmac_f32_e32 v12, 0x3377d1cf, v1
	v_fmac_f32_e32 v12, 0x3f317217, v1
	v_add_f32_e32 v1, 1.0, v198
	v_log_f32_e32 v1, v1
	s_nop 0
	v_mul_f32_e32 v14, 0x3f317217, v1
	v_fma_f32 v14, v1, s77, -v14
	v_fmac_f32_e32 v14, 0x3377d1cf, v1
	v_fmac_f32_e32 v14, 0x3f317217, v1
	v_add_f32_e32 v1, 1.0, v197
	v_log_f32_e32 v1, v1
	s_nop 0
	v_mul_f32_e32 v16, 0x3f317217, v1
	v_fma_f32 v16, v1, s77, -v16
	v_fmac_f32_e32 v16, 0x3377d1cf, v1
	v_fmac_f32_e32 v16, 0x3f317217, v1
	v_add_f32_e32 v1, 1.0, v196
	v_log_f32_e32 v1, v1
	s_nop 0
	v_mul_f32_e32 v18, 0x3f317217, v1
	v_fma_f32 v18, v1, s77, -v18
	v_fmac_f32_e32 v18, 0x3377d1cf, v1
	v_fmac_f32_e32 v18, 0x3f317217, v1
	v_add_f32_e32 v1, 1.0, v195
	v_log_f32_e32 v1, v1
	s_nop 0
	v_mul_f32_e32 v17, 0x3f317217, v1
	v_fma_f32 v17, v1, s77, -v17
	v_fmac_f32_e32 v17, 0x3377d1cf, v1
	v_fmac_f32_e32 v17, 0x3f317217, v1
	v_add_f32_e32 v1, 1.0, v194
	v_pk_add_f32 v[24:25], v[172:173], v[16:17]
	v_log_f32_e32 v1, v1
	s_nop 0
	v_mul_f32_e32 v19, 0x3f317217, v1
	v_fma_f32 v19, v1, s77, -v19
	v_fmac_f32_e32 v19, 0x3377d1cf, v1
	v_fmac_f32_e32 v19, 0x3f317217, v1
	v_add_f32_e32 v1, 1.0, v193
	v_pk_add_f32 v[26:27], v[170:171], v[18:19]
	v_log_f32_e32 v1, v1
	v_pk_add_f32 v[16:17], v[26:27], v[24:25] neg_lo:[1,1] neg_hi:[1,1]
	v_mul_f32_e32 v20, 0x3f317217, v1
	v_fma_f32 v20, v1, s77, -v20
	v_fmac_f32_e32 v20, 0x3377d1cf, v1
	v_fmac_f32_e32 v20, 0x3f317217, v1
	v_pk_add_f32 v[16:17], v[16:17], v[16:17] op_sel:[0,1] op_sel_hi:[1,0]
	ds_bpermute_b32 v18, v181, v16
	v_add_f32_e32 v1, 1.0, v192
	s_waitcnt lgkmcnt(0)
; DI int crow(int i, int h) { return (i & 3) + 8 * (i >> 2) + 4 * h; }
; DI float shx32(float v) { return __shfl_xor(v, 32); }
; template <bool MASKED>
; DI void sb_weights(f32x16 (&Sx)[2], float& carry, int kt, int t, int h) {
;     ...
;         for (int i = 0; i < 16; ++i) {
;           const float z = Sx[mt][i];
;           const bool ok = !MASKED || (kt * 64 + mt * 32 + crow(i, h) < t);
;           const float sp = fmaxf(z, 0.f) + __logf(1.f + __expf(-fabsf(z)));
;           L[i] = ok ? -sp : 0.f;
;           Sx[mt][i] = ok ? (z - sp) : NEG;
;         }
;         float G[4], Go[4];
; #pragma unroll
;         for (int gg = 0; gg < 4; ++gg) { G[gg] = (L[4 * gg] + L[4 * gg + 1]) + (L[4 * gg + 2] + L[4 * gg + 3]); Go[gg] = shx32(G[gg]); }
;         float T[4];
;         T[3] = 0.f; T[2] = G[3] + Go[3]; T[1] = T[2] + (G[2] + Go[2]); T[0] = T[1] + (G[1] + Go[1]);
;         const float tot = T[0] + (G[0] + Go[0]);
; #pragma unroll
;         for (int gg = 0; gg < 4; ++gg) {
;           const float s3 = carry + T[gg] + (h ? 0.f : Go[gg]);
;           const float s2 = s3 + L[4 * gg + 3], s1 = s2 + L[4 * gg + 2], s0 = s1 + L[4 * gg + 1];
;           Sx[mt][4 * gg + 3] = __expf(Sx[mt][4 * gg + 3] + s3);
;           Sx[mt][4 * gg + 2] = __expf(Sx[mt][4 * gg + 2] + s2);
;           Sx[mt][4 * gg + 1] = __expf(Sx[mt][4 * gg + 1] + s1);
;           Sx[mt][4 * gg + 0] = __expf(Sx[mt][4 * gg + 0] + s0);
;         }
;         carry += tot;
	v_cndmask_b32_e32 v9, 0, v18, vcc
	v_log_f32_e32 v1, v1
	s_nop 0
	v_mul_f32_e32 v22, 0x3f317217, v1
	v_fma_f32 v22, v1, s77, -v22
	v_fmac_f32_e32 v22, 0x3377d1cf, v1
	v_fmac_f32_e32 v22, 0x3f317217, v1
	v_add_f32_e32 v1, 1.0, v191
	v_log_f32_e32 v1, v1
	s_nop 0
	v_mul_f32_e32 v21, 0x3f317217, v1
	v_fma_f32 v21, v1, s77, -v21
	v_fmac_f32_e32 v21, 0x3377d1cf, v1
	v_fmac_f32_e32 v21, 0x3f317217, v1
	v_add_f32_e32 v1, 1.0, v190
	v_pk_add_f32 v[20:21], v[168:169], v[20:21]
	v_log_f32_e32 v1, v1
	s_nop 0
	v_mul_f32_e32 v23, 0x3f317217, v1
	v_fma_f32 v23, v1, s77, -v23
	v_fmac_f32_e32 v23, 0x3377d1cf, v1
	v_fmac_f32_e32 v23, 0x3f317217, v1
	v_pk_add_f32 v[22:23], v[166:167], v[22:23]
	v_sub_f32_e32 v1, v93, v27
	v_pk_add_f32 v[28:29], v[22:23], v[20:21] neg_lo:[1,1] neg_hi:[1,1]
	v_sub_f32_e32 v3, v97, v23
	v_add_f32_e32 v5, v28, v29
	ds_bpermute_b32 v7, v181, v5
	v_mov_b32_e32 v28, v25
	v_mov_b32_e32 v29, v27
	v_mov_b32_e32 v27, v25
	v_mov_b32_e32 v25, v26
	s_waitcnt lgkmcnt(0)
	v_add_f32_e32 v166, v5, v7
	v_add_f32_e32 v5, v144, v166
	v_add_f32_e32 v93, v9, v5
	v_pk_add_f32 v[28:29], v[92:93], v[28:29] neg_lo:[0,1] neg_hi:[0,1]
	v_add_f32_e32 v1, v1, v93
	v_mov_b32_e32 v31, v29
	v_mul_f32_e32 v1, 0x3fb8aa3b, v1
	v_pk_add_f32 v[30:31], v[30:31], v[26:27] neg_lo:[0,1] neg_hi:[0,1]
	v_exp_f32_e32 v27, v1
	v_add_f32_e32 v1, v28, v29
	v_mul_f32_e32 v1, 0x3fb8aa3b, v1
	v_mov_b32_e32 v91, v31
	v_exp_f32_e32 v26, v1
	v_add_f32_e32 v1, v30, v31
	v_pk_add_f32 v[90:91], v[90:91], v[24:25] neg_lo:[0,1] neg_hi:[0,1]
	v_mul_f32_e32 v1, 0x3fb8aa3b, v1
	v_exp_f32_e32 v25, v1
	v_add_f32_e32 v1, v90, v91
	v_mul_f32_e32 v1, 0x3fb8aa3b, v1
	v_exp_f32_e32 v24, v1
	v_cndmask_b32_e32 v1, 0, v7, vcc
	v_add_f32_e32 v97, v188, v1
	v_mov_b32_e32 v28, v21
	v_mov_b32_e32 v29, v23
	v_pk_add_f32 v[28:29], v[96:97], v[28:29] neg_lo:[0,1] neg_hi:[0,1]
	v_add_f32_e32 v1, v3, v97
	v_mov_b32_e32 v30, v95
	v_mov_b32_e32 v31, v29
	v_mov_b32_e32 v23, v21
	v_mul_f32_e32 v1, 0x3fb8aa3b, v1
	v_pk_add_f32 v[90:91], v[30:31], v[22:23] neg_lo:[0,1] neg_hi:[0,1]
	v_exp_f32_e32 v31, v1
	v_add_f32_e32 v1, v28, v29
	v_mul_f32_e32 v1, 0x3fb8aa3b, v1
	v_mov_b32_e32 v95, v91
	v_mov_b32_e32 v21, v22
	v_exp_f32_e32 v30, v1
	v_add_f32_e32 v1, v90, v91
	v_pk_add_f32 v[20:21], v[94:95], v[20:21] neg_lo:[0,1] neg_hi:[0,1]
	v_mul_f32_e32 v1, 0x3fb8aa3b, v1
	v_exp_f32_e32 v29, v1
	v_add_f32_e32 v1, v20, v21
	v_mul_f32_e32 v1, 0x3fb8aa3b, v1
	v_exp_f32_e32 v28, v1
	v_add_f32_e32 v1, 1.0, v189
	v_log_f32_e32 v1, v1
	s_nop 0
	v_mul_f32_e32 v20, 0x3f317217, v1
	v_fma_f32 v20, v1, s77, -v20
	v_fmac_f32_e32 v20, 0x3377d1cf, v1
	v_fmac_f32_e32 v20, 0x3f317217, v1
	v_add_f32_e32 v1, 1.0, v187
	v_log_f32_e32 v1, v1
	s_nop 0
	v_mul_f32_e32 v22, 0x3f317217, v1
	v_fma_f32 v22, v1, s77, -v22
	v_fmac_f32_e32 v22, 0x3377d1cf, v1
	v_fmac_f32_e32 v22, 0x3f317217, v1
	v_add_f32_e32 v1, 1.0, v186
	v_log_f32_e32 v1, v1
	s_nop 0
	v_mul_f32_e32 v21, 0x3f317217, v1
	v_fma_f32 v21, v1, s77, -v21
	v_fmac_f32_e32 v21, 0x3377d1cf, v1
	v_fmac_f32_e32 v21, 0x3f317217, v1
	v_exp_f32_e32 v1, v185
	v_pk_add_f32 v[96:97], v[162:163], v[20:21]
	v_add_f32_e32 v1, 1.0, v1
	v_log_f32_e32 v1, v1
	s_nop 0
	v_mul_f32_e32 v23, 0x3f317217, v1
	v_fma_f32 v23, v1, s77, -v23
	v_fmac_f32_e32 v23, 0x3377d1cf, v1
	v_fmac_f32_e32 v23, 0x3f317217, v1
	v_exp_f32_e32 v1, v184
	v_pk_add_f32 v[162:163], v[164:165], v[22:23]
	v_add_f32_e32 v1, 1.0, v1
	v_pk_add_f32 v[20:21], v[162:163], v[96:97] neg_lo:[1,1] neg_hi:[1,1]
	v_sub_f32_e32 v170, v69, v163
	v_log_f32_e32 v1, v1
	s_nop 0
	v_mul_f32_e32 v3, 0x3f317217, v1
	v_fma_f32 v3, v1, s77, -v3
	v_fmac_f32_e32 v3, 0x3377d1cf, v1
	v_fmac_f32_e32 v3, 0x3f317217, v1
	v_mov_b32_e32 v1, v3
	v_exp_f32_e32 v3, v183
	v_pk_add_f32 v[160:161], v[160:161], v[0:1]
	v_add_f32_e32 v3, 1.0, v3
	v_log_f32_e32 v3, v3
	s_nop 0
	v_mul_f32_e32 v5, 0x3f317217, v3
	v_fma_f32 v5, v3, s77, -v5
	v_fmac_f32_e32 v5, 0x3377d1cf, v3
	v_fmac_f32_e32 v5, 0x3f317217, v3
	v_mov_b32_e32 v3, v5
	v_exp_f32_e32 v5, v182
	v_pk_add_f32 v[158:159], v[158:159], v[2:3]
	v_add_f32_e32 v5, 1.0, v5
	v_pk_add_f32 v[0:1], v[158:159], v[160:161] neg_lo:[1,1] neg_hi:[1,1]
	v_log_f32_e32 v5, v5
	s_nop 0
	v_mul_f32_e32 v7, 0x3f317217, v5
	v_fma_f32 v7, v5, s77, -v7
	v_fmac_f32_e32 v7, 0x3377d1cf, v5
	v_fmac_f32_e32 v7, 0x3f317217, v5
	v_mov_b32_e32 v5, v7
	v_exp_f32_e32 v7, v153
	v_max_f32_e32 v153, 0, v151
	v_max_f32_e32 v151, 0, v147
	v_pk_add_f32 v[4:5], v[156:157], v[4:5]
	v_add_f32_e32 v7, 1.0, v7
	v_log_f32_e32 v7, v7
	s_nop 0
	v_mul_f32_e32 v9, 0x3f317217, v7
	v_fma_f32 v9, v7, s77, -v9
	v_fmac_f32_e32 v9, 0x3377d1cf, v7
	v_fmac_f32_e32 v9, 0x3f317217, v7
	v_mov_b32_e32 v7, v9
	v_exp_f32_e32 v9, v149
	v_pk_add_f32 v[6:7], v[154:155], v[6:7]
	v_add_f32_e32 v9, 1.0, v9
	v_pk_add_f32 v[2:3], v[6:7], v[4:5] neg_lo:[1,1] neg_hi:[1,1]
	v_sub_f32_e32 v171, v85, v6
	v_log_f32_e32 v9, v9
	v_pk_add_f32 v[0:1], v[0:1], v[2:3]
	ds_bpermute_b32 v2, v181, v0
	ds_bpermute_b32 v3, v181, v1
	v_mul_f32_e32 v11, 0x3f317217, v9
	v_fma_f32 v11, v9, s77, -v11
	v_fmac_f32_e32 v11, 0x3377d1cf, v9
	v_fmac_f32_e32 v11, 0x3f317217, v9
	s_waitcnt lgkmcnt(1)
	v_cndmask_b32_e32 v85, 0, v2, vcc
	s_waitcnt lgkmcnt(0)
; DI int crow(int i, int h) { return (i & 3) + 8 * (i >> 2) + 4 * h; }
; DI float shx32(float v) { return __shfl_xor(v, 32); }
; template <bool MASKED>
; DI void sb_weights(f32x16 (&Sx)[2], float& carry, int kt, int t, int h) {
;     ...
;         for (int i = 0; i < 16; ++i) {
;           const float z = Sx[mt][i];
;           const bool ok = !MASKED || (kt * 64 + mt * 32 + crow(i, h) < t);
;           const float sp = fmaxf(z, 0.f) + __logf(1.f + __expf(-fabsf(z)));
;           L[i] = ok ? -sp : 0.f;
;           Sx[mt][i] = ok ? (z - sp) : NEG;
;         }
;         float G[4], Go[4];
; #pragma unroll
;         for (int gg = 0; gg < 4; ++gg) { G[gg] = (L[4 * gg] + L[4 * gg + 1]) + (L[4 * gg + 2] + L[4 * gg + 3]); Go[gg] = shx32(G[gg]); }
;         float T[4];
;         T[3] = 0.f; T[2] = G[3] + Go[3]; T[1] = T[2] + (G[2] + Go[2]); T[0] = T[1] + (G[1] + Go[1]);
	v_pk_add_f32 v[0:1], v[0:1], v[2:3]
	v_mov_b32_e32 v9, v11
	v_exp_f32_e32 v11, v145
	v_pk_add_f32 v[8:9], v[152:153], v[8:9]
	v_add_f32_e32 v11, 1.0, v11
	v_mov_b32_e32 v156, v8
	v_log_f32_e32 v11, v11
	s_nop 0
	v_mul_f32_e32 v13, 0x3f317217, v11
	v_fma_f32 v13, v11, s77, -v13
	v_fmac_f32_e32 v13, 0x3377d1cf, v11
	v_fmac_f32_e32 v13, 0x3f317217, v11
	v_mov_b32_e32 v11, v13
	v_max_f32_e32 v13, v76, v76
	v_max_f32_e32 v149, 0, v13
	v_mul_f32_e64 v13, |v76|, s76
	v_exp_f32_e32 v13, v13
	v_pk_add_f32 v[10:11], v[150:151], v[10:11]
	v_mov_b32_e32 v150, v160
	v_mov_b32_e32 v151, v158
	v_add_f32_e32 v13, 1.0, v13
	v_mov_b32_e32 v154, v10
	v_mov_b32_e32 v157, v10
	v_log_f32_e32 v13, v13
	s_nop 0
	v_mul_f32_e32 v15, 0x3f317217, v13
	v_fma_f32 v15, v13, s77, -v15
	v_fmac_f32_e32 v15, 0x3377d1cf, v13
	v_fmac_f32_e32 v15, 0x3f317217, v13
	v_mov_b32_e32 v13, v15
	v_max_f32_e32 v15, v77, v77
	v_max_f32_e32 v147, 0, v15
	v_mul_f32_e64 v15, |v77|, s76
	v_exp_f32_e32 v15, v15
	v_pk_add_f32 v[12:13], v[148:149], v[12:13]
	v_mov_b32_e32 v148, v158
	v_mov_b32_e32 v149, v4
	v_add_f32_e32 v15, 1.0, v15
	v_mov_b32_e32 v152, v12
	v_mov_b32_e32 v155, v12
	v_log_f32_e32 v15, v15
	v_mov_b32_e32 v158, v161
	v_mul_f32_e32 v17, 0x3f317217, v15
	v_fma_f32 v17, v15, s77, -v17
	v_fmac_f32_e32 v17, 0x3377d1cf, v15
	v_fmac_f32_e32 v17, 0x3f317217, v15
	v_mov_b32_e32 v15, v17
	v_max_f32_e32 v17, v78, v78
	v_max_f32_e32 v90, 0, v17
	v_mul_f32_e64 v17, |v78|, s76
	v_exp_f32_e32 v17, v17
	v_pk_add_f32 v[14:15], v[146:147], v[14:15]
	v_mov_b32_e32 v147, v6
	v_pk_add_f32 v[22:23], v[14:15], v[12:13] neg_lo:[1,1] neg_hi:[1,1]
	v_add_f32_e32 v17, 1.0, v17
	v_cndmask_b32_e32 v6, 0, v3, vcc
	v_mov_b32_e32 v146, v4
	v_log_f32_e32 v17, v17
	v_sub_f32_e32 v172, v89, v14
	v_mov_b32_e32 v153, v14
	v_sub_f32_e32 v160, v77, v15
	v_mul_f32_e32 v92, 0x3f317217, v17
	v_fma_f32 v92, v17, s77, -v92
	v_fmac_f32_e32 v92, 0x3377d1cf, v17
	v_fmac_f32_e32 v92, 0x3f317217, v17
	v_mov_b32_e32 v14, v13
	v_max_f32_e32 v17, v79, v79
	v_max_f32_e32 v91, 0, v17
	v_mul_f32_e64 v17, |v79|, s76
	v_exp_f32_e32 v17, v17
	s_nop 0
	v_add_f32_e32 v17, 1.0, v17
	v_log_f32_e32 v17, v17
	s_nop 0
	v_mul_f32_e32 v93, 0x3f317217, v17
	v_fma_f32 v93, v17, s77, -v93
	v_fmac_f32_e32 v93, 0x3377d1cf, v17
	v_fmac_f32_e32 v93, 0x3f317217, v17
	v_max_f32_e32 v17, v80, v80
	v_max_f32_e32 v94, 0, v17
	v_mul_f32_e64 v17, |v80|, s76
	v_exp_f32_e32 v17, v17
	v_pk_add_f32 v[90:91], v[90:91], v[92:93]
	v_add_f32_e32 v17, 1.0, v17
	v_log_f32_e32 v17, v17
	s_nop 0
	v_mul_f32_e32 v168, 0x3f317217, v17
	v_fma_f32 v168, v17, s77, -v168
	v_fmac_f32_e32 v168, 0x3377d1cf, v17
	v_fmac_f32_e32 v168, 0x3f317217, v17
	v_max_f32_e32 v17, v81, v81
	v_max_f32_e32 v95, 0, v17
	v_mul_f32_e64 v17, |v81|, s76
	v_exp_f32_e32 v17, v17
	s_nop 0
	v_add_f32_e32 v17, 1.0, v17
	v_log_f32_e32 v17, v17
	s_nop 0
	v_mul_f32_e32 v169, 0x3f317217, v17
	v_fma_f32 v169, v17, s77, -v169
	v_fmac_f32_e32 v169, 0x3377d1cf, v17
	v_fmac_f32_e32 v169, 0x3f317217, v17
	v_add_f32_e32 v17, v20, v21
	ds_bpermute_b32 v19, v181, v17
	v_pk_add_f32 v[94:95], v[94:95], v[168:169]
	v_pk_add_f32 v[20:21], v[10:11], v[8:9] neg_lo:[1,1] neg_hi:[1,1]
	v_sub_f32_e32 v8, v73, v7
	v_pk_add_f32 v[20:21], v[20:21], v[22:23]
	s_waitcnt lgkmcnt(0)
	v_add_f32_e32 v145, v17, v19
	v_cndmask_b32_e32 v69, 0, v19, vcc
	v_sub_f32_e64 v19, -v95, v94
	v_sub_f32_e64 v17, -v91, v90
	v_pk_add_f32 v[2:3], v[16:17], v[18:19]
	ds_bpermute_b32 v22, v181, v20
	ds_bpermute_b32 v23, v181, v21
	ds_bpermute_b32 v167, v181, v3
	v_mov_b32_e32 v16, v83
	v_sub_f32_e32 v168, v81, v95
	s_waitcnt lgkmcnt(2)
	v_cndmask_b32_e32 v4, 0, v22, vcc
	s_waitcnt lgkmcnt(1)
	v_pk_add_f32 v[20:21], v[20:21], v[22:23]
	s_waitcnt lgkmcnt(0)
; template <bool MASKED>
; DI void sb_weights(f32x16 (&Sx)[2], float& carry, int kt, int t, int h) {
;     ...
;         T[3] = 0.f; T[2] = G[3] + Go[3]; T[1] = T[2] + (G[2] + Go[2]); T[0] = T[1] + (G[1] + Go[1]);
;         const float tot = T[0] + (G[0] + Go[0]);
; #pragma unroll
;         for (int gg = 0; gg < 4; ++gg) {
;           const float s3 = carry + T[gg] + (h ? 0.f : Go[gg]);
;           const float s2 = s3 + L[4 * gg + 3], s1 = s2 + L[4 * gg + 2], s0 = s1 + L[4 * gg + 1];
;           Sx[mt][4 * gg + 3] = __expf(Sx[mt][4 * gg + 3] + s3);
;           Sx[mt][4 * gg + 2] = __expf(Sx[mt][4 * gg + 2] + s2);
;           Sx[mt][4 * gg + 1] = __expf(Sx[mt][4 * gg + 1] + s1);
;           Sx[mt][4 * gg + 0] = __expf(Sx[mt][4 * gg + 0] + s0);
;         }
;         carry += tot;
	v_pk_add_f32 v[92:93], v[2:3], v[166:167]
	v_cndmask_b32_e32 v10, 0, v23, vcc
	v_pk_add_f32 v[164:165], v[20:21], v[92:93]
	s_nop 0
	v_add_f32_e32 v2, v144, v164
	v_add_f32_e32 v85, v85, v2
	v_pk_add_f32 v[2:3], v[84:85], v[146:147] neg_lo:[0,1] neg_hi:[0,1]
	v_pk_add_f32 v[0:1], v[0:1], v[164:165]
	v_mov_b32_e32 v17, v3
	v_add_f32_e32 v2, v2, v3
	v_pk_add_f32 v[16:17], v[16:17], v[148:149] neg_lo:[0,1] neg_hi:[0,1]
	v_mul_f32_e32 v2, 0x3fb8aa3b, v2
	v_mov_b32_e32 v83, v17
	v_exp_f32_e32 v18, v2
	v_add_f32_e32 v2, v16, v17
	v_pk_add_f32 v[20:21], v[82:83], v[150:151] neg_lo:[0,1] neg_hi:[0,1]
	v_mul_f32_e32 v2, 0x3fb8aa3b, v2
	v_exp_f32_e32 v17, v2
	v_add_f32_e32 v2, v20, v21
	v_mul_f32_e32 v2, 0x3fb8aa3b, v2
	v_exp_f32_e32 v16, v2
	v_add_f32_e32 v2, v144, v92
	v_add_f32_e32 v89, v4, v2
	v_pk_add_f32 v[2:3], v[88:89], v[152:153] neg_lo:[0,1] neg_hi:[0,1]
	v_mov_b32_e32 v20, v87
	v_mov_b32_e32 v21, v3
	v_add_f32_e32 v2, v2, v3
	v_pk_add_f32 v[20:21], v[20:21], v[154:155] neg_lo:[0,1] neg_hi:[0,1]
	v_mul_f32_e32 v2, 0x3fb8aa3b, v2
	v_mov_b32_e32 v87, v21
	v_exp_f32_e32 v22, v2
	v_add_f32_e32 v2, v20, v21
	v_pk_add_f32 v[82:83], v[86:87], v[156:157] neg_lo:[0,1] neg_hi:[0,1]
	v_mul_f32_e32 v2, 0x3fb8aa3b, v2
	v_exp_f32_e32 v21, v2
	v_add_f32_e32 v2, v82, v83
	v_pk_add_f32 v[82:83], v[144:145], v[0:1]
	v_mul_f32_e32 v2, 0x3fb8aa3b, v2
	v_add_f32_e32 v0, v82, v1
	v_add_f32_e32 v69, v69, v0
	v_mov_b32_e32 v0, v97
	v_mov_b32_e32 v1, v163
	v_pk_add_f32 v[0:1], v[68:69], v[0:1] neg_lo:[0,1] neg_hi:[0,1]
	v_exp_f32_e32 v20, v2
	v_mov_b32_e32 v2, v67
	v_mov_b32_e32 v3, v1
	v_mov_b32_e32 v163, v97
	v_add_f32_e32 v12, v171, v85
	v_add_f32_e32 v4, v172, v89
	v_pk_add_f32 v[84:85], v[2:3], v[162:163] neg_lo:[0,1] neg_hi:[0,1]
	v_add_f32_e32 v2, v170, v69
	v_add_f32_e32 v0, v0, v1
	v_mul_f32_e32 v4, 0x3fb8aa3b, v4
	v_mul_f32_e32 v2, 0x3fb8aa3b, v2
	v_mul_f32_e32 v0, 0x3fb8aa3b, v0
	v_exp_f32_e32 v23, v4
	v_mov_b32_e32 v67, v85
	v_mov_b32_e32 v97, v162
	v_exp_f32_e32 v3, v2
	v_exp_f32_e32 v2, v0
	v_add_f32_e32 v0, v84, v85
	v_add_f32_e32 v4, v82, v165
	v_pk_add_f32 v[66:67], v[66:67], v[96:97] neg_lo:[0,1] neg_hi:[0,1]
	v_mul_f32_e32 v0, 0x3fb8aa3b, v0
	v_add_f32_e32 v73, v6, v4
	v_mov_b32_e32 v6, v5
	v_exp_f32_e32 v1, v0
	v_add_f32_e32 v0, v66, v67
	v_pk_add_f32 v[66:67], v[72:73], v[6:7] neg_lo:[0,1] neg_hi:[0,1]
	v_mov_b32_e32 v6, v71
	v_mov_b32_e32 v7, v67
	v_mov_b32_e32 v4, v159
	v_pk_add_f32 v[4:5], v[6:7], v[4:5] neg_lo:[0,1] neg_hi:[0,1]
	v_add_f32_e32 v6, v8, v73
	v_add_f32_e32 v8, v93, v82
	v_add_f32_e32 v77, v10, v8
	v_mul_f32_e32 v12, 0x3fb8aa3b, v12
	v_mul_f32_e32 v6, 0x3fb8aa3b, v6
	v_pk_add_f32 v[14:15], v[76:77], v[14:15] neg_lo:[0,1] neg_hi:[0,1]
	v_exp_f32_e32 v19, v12
	v_exp_f32_e32 v7, v6
	v_add_f32_e32 v6, v66, v67
	v_mov_b32_e32 v66, v75
	v_mov_b32_e32 v67, v15
	v_mov_b32_e32 v12, v11
	v_pk_add_f32 v[12:13], v[66:67], v[12:13] neg_lo:[0,1] neg_hi:[0,1]
	v_add_f32_e32 v8, v160, v77
	v_mov_b32_e32 v75, v13
	v_mov_b32_e32 v10, v9
	v_mul_f32_e32 v8, 0x3fb8aa3b, v8
	v_pk_add_f32 v[66:67], v[74:75], v[10:11] neg_lo:[0,1] neg_hi:[0,1]
	v_exp_f32_e32 v11, v8
	v_add_f32_e32 v8, v14, v15
	v_mul_f32_e32 v8, 0x3fb8aa3b, v8
	v_exp_f32_e32 v10, v8
	v_add_f32_e32 v8, v12, v13
	v_add_f32_e32 v12, 0, v82
	v_cndmask_b32_e32 v13, 0, v167, vcc
	v_add_f32_e32 v81, v13, v12
	v_mul_f32_e32 v8, 0x3fb8aa3b, v8
	v_pk_add_f32 v[12:13], v[80:81], v[94:95] neg_lo:[0,1] neg_hi:[0,1]
	v_exp_f32_e32 v9, v8
	v_add_f32_e32 v8, v66, v67
	v_mov_b32_e32 v14, v79
	v_mov_b32_e32 v15, v13
	v_pk_mov_b32 v[66:67], v[90:91], v[94:95] op_sel:[1,0]
	v_add_f32_e32 v12, v12, v13
	v_pk_add_f32 v[66:67], v[14:15], v[66:67] neg_lo:[0,1] neg_hi:[0,1]
	v_add_f32_e32 v14, v168, v81
	v_mov_b32_e32 v71, v5
	v_add_f32_e32 v4, v4, v5
	v_mul_f32_e32 v14, 0x3fb8aa3b, v14
	v_mul_f32_e32 v12, 0x3fb8aa3b, v12
	v_pk_add_f32 v[68:69], v[70:71], v[158:159] neg_lo:[0,1] neg_hi:[0,1]
	v_mul_f32_e32 v4, 0x3fb8aa3b, v4
	v_mov_b32_e32 v79, v67
	v_exp_f32_e32 v15, v14
	v_exp_f32_e32 v14, v12
	v_add_f32_e32 v12, v66, v67
	v_exp_f32_e32 v5, v4
	v_add_f32_e32 v4, v68, v69
	v_pk_add_f32 v[68:69], v[78:79], v[90:91] neg_lo:[0,1] neg_hi:[0,1]
	v_mul_f32_e32 v12, 0x3fb8aa3b, v12
	v_exp_f32_e32 v13, v12
	v_add_f32_e32 v12, v68, v69
	v_mul_f32_e32 v0, 0x3fb8aa3b, v0
	v_mul_f32_e32 v6, 0x3fb8aa3b, v6
	v_mul_f32_e32 v4, 0x3fb8aa3b, v4
	v_mul_f32_e32 v8, 0x3fb8aa3b, v8
	v_mul_f32_e32 v12, 0x3fb8aa3b, v12
	v_exp_f32_e32 v0, v0
	v_exp_f32_e32 v6, v6
	v_exp_f32_e32 v4, v4
	v_exp_f32_e32 v8, v8
	v_exp_f32_e32 v12, v12
	v_add_f32_e32 v144, v82, v83
